# attention: next tile's global loads issued right after staging writes (before the barrier); -c2 copy used as QK accumulator init, packed row sums (on top of v82)
# speedup vs baseline: 1.0106x; 1.0076x over previous
.LBB0_503:
	s_or_b64 exec, exec, s[54:55]
	s_lshl_b32 s3, s98, 5
	s_ashr_i32 s54, s3, 31
	s_add_u32 s12, s3, s12
	v_and_b32_e32 v186, 31, v154
	s_addc_u32 s54, s54, 0
	s_waitcnt vmcnt(8)
	v_or_b32_e32 v156, s12, v186
	v_mov_b32_e32 v157, s54
	s_add_u32 s54, s85, s57
	v_lshlrev_b64 v[2:3], 14, v[156:157]
	v_lshrrev_b32_e32 v121, 5, v185
	s_addc_u32 s55, s86, 0
	s_add_i32 s33, s33, -16
	v_lshl_add_u64 v[2:3], s[10:11], 0, v[2:3]
	s_add_u32 vcc_lo, s10, s14
	v_lshlrev_b32_e32 v187, 4, v154
	v_lshl_add_u64 v[2:3], v[2:3], 0, s[14:15]
	v_lshlrev_b32_e32 v162, 4, v121
	v_mov_b32_e32 v163, v129
	s_addc_u32 vcc_hi, s11, 0
	v_and_b32_e32 v128, 0xf0, v187
	v_lshl_add_u64 v[2:3], v[2:3], 0, v[162:163]
	v_lshl_add_u64 v[160:161], vcc, 0, v[128:129]
	v_ashrrev_i32_e32 v119, 4, v154
	v_lshl_add_u64 v[52:53], v[2:3], 0, s[36:37]
	v_add_co_u32_e32 v2, vcc, s65, v2
	v_add_u32_e32 v1, s56, v119
	s_nop 0
	v_addc_co_u32_e32 v3, vcc, 0, v3, vcc
	v_mov_b32_e32 v6, s33
	v_cmp_lt_i32_e32 vcc, 15, v1
	v_min_i32_e32 v0, 0x80f, v1
	global_load_dwordx4 v[80:83], v[2:3], off
	global_load_dwordx4 v[86:89], v[52:53], off offset:224
	v_cndmask_b32_e32 v1, v179, v6, vcc
	v_add_u32_e32 v2, v1, v0
	v_ashrrev_i32_e32 v3, 31, v2
	v_lshlrev_b64 v[2:3], 14, v[2:3]
	v_lshl_add_u64 v[2:3], v[160:161], 0, v[2:3]
	v_add_co_u32_e32 v4, vcc, s65, v2
	v_ashrrev_i32_e32 v1, 31, v0
	s_nop 0
	v_addc_co_u32_e32 v5, vcc, 0, v3, vcc
	v_add_co_u32_e32 v2, vcc, s63, v2
	v_lshl_add_u64 v[0:1], v[0:1], 2, s[54:55]
	s_nop 0
	v_addc_co_u32_e32 v3, vcc, 0, v3, vcc
	global_load_dwordx4 v[96:99], v[52:53], off offset:160
	global_load_dwordx4 v[100:103], v[52:53], off offset:192
	global_load_dwordx4 v[12:15], v[4:5], off offset:2048
	global_load_dwordx4 v[8:11], v[2:3], off
	v_add_u32_e32 v2, 0x200, v154
	v_ashrrev_i32_e32 v189, 4, v2
	v_add_u32_e32 v3, s56, v189
	v_cmp_lt_i32_e32 vcc, 15, v3
	v_min_i32_e32 v2, 0x80f, v3
	v_mul_lo_u32 v48, v48, s66
	v_cndmask_b32_e32 v3, v179, v6, vcc
	v_add_u32_e32 v4, v3, v2
	v_ashrrev_i32_e32 v5, 31, v4
	v_lshlrev_b64 v[4:5], 14, v[4:5]
	v_lshl_add_u64 v[54:55], v[160:161], 0, v[4:5]
	v_add_co_u32_e32 v4, vcc, s65, v54
	v_ashrrev_i32_e32 v3, 31, v2
	s_nop 0
	v_addc_co_u32_e32 v5, vcc, 0, v55, vcc
	global_load_dword v120, v[0:1], off
	s_nop 0
	global_load_dwordx4 v[4:7], v[4:5], off offset:2048
	v_add_co_u32_e32 v0, vcc, s63, v54
	v_add3_u32 v48, s67, v48, v50
	s_nop 0
	v_addc_co_u32_e32 v1, vcc, 0, v55, vcc
	v_lshl_add_u64 v[54:55], v[2:3], 2, s[54:55]
	global_load_dwordx4 v[0:3], v[0:1], off
	s_nop 0
	global_load_dword v118, v[54:55], off
	global_load_dwordx4 v[172:175], v[52:53], off offset:32
	global_load_dwordx4 v[164:167], v[52:53], off offset:64
	global_load_dwordx4 v[148:151], v[52:53], off offset:96
	global_load_dwordx4 v[140:143], v[52:53], off offset:128
	s_waitcnt vmcnt(19)
	ds_write2_b64 v48, v[36:37], v[38:39] offset1:1
	ds_write2_b64 v48, v[32:33], v[34:35] offset0:2 offset1:3
	ds_write2_b64 v48, v[24:25], v[26:27] offset0:4 offset1:5
	s_waitcnt vmcnt(15)
	ds_write2_b64 v48, v[44:45], v[46:47] offset0:6 offset1:7
	s_waitcnt vmcnt(14)
	ds_write2_b64 v48, v[40:41], v[42:43] offset0:8 offset1:9
	ds_write2_b64 v48, v[28:29], v[30:31] offset0:10 offset1:11
	ds_write2_b64 v48, v[20:21], v[22:23] offset0:12 offset1:13
	ds_write2_b64 v48, v[16:17], v[18:19] offset0:14 offset1:15
	v_and_b32_e32 v16, 32, v185
	v_add_u32_e32 v16, 0, v16
	v_add_u32_e32 v16, 0x25e00, v16
	ds_read_b128 v[76:79], v16
	ds_read_b128 v[72:75], v16 offset:16
	ds_read_b128 v[68:71], v16 offset:64
	ds_read_b128 v[64:67], v16 offset:80
	ds_read_b128 v[60:63], v16 offset:128
	ds_read_b128 v[56:59], v16 offset:144
	ds_read_b128 v[52:55], v16 offset:192
	ds_read_b128 v[48:51], v16 offset:208
	ds_read_b128 v[44:47], v16 offset:256
	ds_read_b128 v[40:43], v16 offset:272
	ds_read_b128 v[36:39], v16 offset:320
	ds_read_b128 v[32:35], v16 offset:336
	ds_read_b128 v[28:31], v16 offset:384
	ds_read_b128 v[24:27], v16 offset:400
	ds_read_b128 v[20:23], v16 offset:448
	ds_read_b128 v[16:19], v16 offset:464
	s_waitcnt vmcnt(13)
	v_and_b32_e32 v177, 0xffff0000, v80
	s_waitcnt vmcnt(12)
	v_and_b32_e32 v85, 0xffff0000, v89
	v_lshlrev_b32_e32 v122, 16, v89
	v_lshlrev_b32_e32 v110, 16, v88
	v_and_b32_e32 v89, 0xffff0000, v88
	v_mov_b32_e32 v88, v85
	v_and_b32_e32 v93, 0xffff0000, v87
	v_mov_b32_e32 v123, v110
	v_pk_mul_f32 v[90:91], v[88:89], v[88:89]
	v_lshlrev_b32_e32 v124, 16, v87
	v_lshlrev_b32_e32 v108, 16, v86
	v_and_b32_e32 v87, 0xffff0000, v86
	v_mov_b32_e32 v86, v93
	v_pk_fma_f32 v[190:191], v[122:123], v[122:123], v[90:91]
	v_mov_b32_e32 v125, v108
	v_pk_mul_f32 v[90:91], v[86:87], v[86:87]
	s_waitcnt vmcnt(10)
	v_and_b32_e32 v131, 0xffff0000, v101
	v_pk_fma_f32 v[192:193], v[124:125], v[124:125], v[90:91]
	v_and_b32_e32 v91, 0xffff0000, v103
	v_lshlrev_b32_e32 v106, 16, v102
	v_and_b32_e32 v95, 0xffff0000, v102
	v_mov_b32_e32 v94, v91
	v_lshlrev_b32_e32 v130, 16, v101
	v_mul_f32_e32 v84, v131, v131
	v_and_b32_e32 v105, 0xffff0000, v100
	v_lshlrev_b32_e32 v126, 16, v103
	v_mov_b32_e32 v127, v106
	v_pk_mul_f32 v[102:103], v[94:95], v[94:95]
	v_pk_fma_f32 v[196:197], v[130:131], v[130:131], v[84:85] op_sel_hi:[1,1,0]
	v_lshlrev_b32_e32 v104, 16, v100
	v_mul_f32_e32 v84, v105, v105
	v_and_b32_e32 v133, 0xffff0000, v99
	v_pk_fma_f32 v[194:195], v[126:127], v[126:127], v[102:103]
	v_pk_fma_f32 v[198:199], v[104:105], v[104:105], v[84:85] op_sel_hi:[1,1,0]
	v_lshlrev_b32_e32 v132, 16, v99
	v_mul_f32_e32 v84, v133, v133
	v_and_b32_e32 v103, 0xffff0000, v98
	v_pk_fma_f32 v[200:201], v[132:133], v[132:133], v[84:85] op_sel_hi:[1,1,0]
	v_lshlrev_b32_e32 v102, 16, v98
	v_mul_f32_e32 v84, v103, v103
	v_and_b32_e32 v135, 0xffff0000, v97
	v_pk_fma_f32 v[202:203], v[102:103], v[102:103], v[84:85] op_sel_hi:[1,1,0]
	v_lshlrev_b32_e32 v134, 16, v97
	v_mul_f32_e32 v84, v135, v135
	v_and_b32_e32 v101, 0xffff0000, v96
	v_pk_fma_f32 v[204:205], v[134:135], v[134:135], v[84:85] op_sel_hi:[1,1,0]
	v_lshlrev_b32_e32 v100, 16, v96
	v_mul_f32_e32 v84, v101, v101
	s_waitcnt vmcnt(0)
	v_and_b32_e32 v137, 0xffff0000, v143
	v_pk_fma_f32 v[206:207], v[100:101], v[100:101], v[84:85] op_sel_hi:[1,1,0]
	v_lshlrev_b32_e32 v136, 16, v143
	v_mul_f32_e32 v84, v137, v137
	v_and_b32_e32 v99, 0xffff0000, v142
	v_pk_fma_f32 v[208:209], v[136:137], v[136:137], v[84:85] op_sel_hi:[1,1,0]
	v_lshlrev_b32_e32 v98, 16, v142
	v_mul_f32_e32 v84, v99, v99
	v_and_b32_e32 v139, 0xffff0000, v141
	v_pk_fma_f32 v[210:211], v[98:99], v[98:99], v[84:85] op_sel_hi:[1,1,0]
	v_lshlrev_b32_e32 v138, 16, v141
	v_mul_f32_e32 v84, v139, v139
	v_and_b32_e32 v97, 0xffff0000, v140
	v_pk_fma_f32 v[212:213], v[138:139], v[138:139], v[84:85] op_sel_hi:[1,1,0]
	v_lshlrev_b32_e32 v96, 16, v140
	v_mul_f32_e32 v84, v97, v97
	v_and_b32_e32 v141, 0xffff0000, v151
	v_pk_fma_f32 v[214:215], v[96:97], v[96:97], v[84:85] op_sel_hi:[1,1,0]
	v_lshlrev_b32_e32 v140, 16, v151
	v_mul_f32_e32 v84, v141, v141
	v_and_b32_e32 v143, 0xffff0000, v150
	v_pk_fma_f32 v[216:217], v[140:141], v[140:141], v[84:85] op_sel_hi:[1,1,0]
	v_lshlrev_b32_e32 v142, 16, v150
	v_mul_f32_e32 v84, v143, v143
	v_and_b32_e32 v145, 0xffff0000, v149
	v_pk_fma_f32 v[218:219], v[142:143], v[142:143], v[84:85] op_sel_hi:[1,1,0]
	v_lshlrev_b32_e32 v144, 16, v149
	v_mul_f32_e32 v84, v145, v145
	v_and_b32_e32 v147, 0xffff0000, v148
	v_pk_fma_f32 v[220:221], v[144:145], v[144:145], v[84:85] op_sel_hi:[1,1,0]
	v_lshlrev_b32_e32 v146, 16, v148
	v_mul_f32_e32 v84, v147, v147
	v_and_b32_e32 v149, 0xffff0000, v167
	v_pk_fma_f32 v[222:223], v[146:147], v[146:147], v[84:85] op_sel_hi:[1,1,0]
	v_lshlrev_b32_e32 v148, 16, v167
	v_mul_f32_e32 v84, v149, v149
	v_and_b32_e32 v151, 0xffff0000, v166
	v_pk_fma_f32 v[224:225], v[148:149], v[148:149], v[84:85] op_sel_hi:[1,1,0]
	v_lshlrev_b32_e32 v150, 16, v166
	v_mul_f32_e32 v84, v151, v151
	v_and_b32_e32 v153, 0xffff0000, v165
	v_pk_fma_f32 v[226:227], v[150:151], v[150:151], v[84:85] op_sel_hi:[1,1,0]
	v_lshlrev_b32_e32 v152, 16, v165
	v_mul_f32_e32 v84, v153, v153
	v_and_b32_e32 v159, 0xffff0000, v164
	v_pk_fma_f32 v[228:229], v[152:153], v[152:153], v[84:85] op_sel_hi:[1,1,0]
	v_lshlrev_b32_e32 v158, 16, v164
	v_mul_f32_e32 v84, v159, v159
	v_and_b32_e32 v165, 0xffff0000, v175
	v_pk_fma_f32 v[230:231], v[158:159], v[158:159], v[84:85] op_sel_hi:[1,1,0]
	v_lshlrev_b32_e32 v164, 16, v175
	v_mul_f32_e32 v84, v165, v165
	v_and_b32_e32 v167, 0xffff0000, v174
	v_pk_fma_f32 v[232:233], v[164:165], v[164:165], v[84:85] op_sel_hi:[1,1,0]
	v_lshlrev_b32_e32 v166, 16, v174
	v_mul_f32_e32 v84, v167, v167
	v_and_b32_e32 v169, 0xffff0000, v173
	v_pk_fma_f32 v[234:235], v[166:167], v[166:167], v[84:85] op_sel_hi:[1,1,0]
	v_lshlrev_b32_e32 v168, 16, v173
	v_mul_f32_e32 v84, v169, v169
	v_and_b32_e32 v171, 0xffff0000, v172
	v_and_b32_e32 v175, 0xffff0000, v82
	v_pk_fma_f32 v[236:237], v[168:169], v[168:169], v[84:85] op_sel_hi:[1,1,0]
	v_lshlrev_b32_e32 v170, 16, v172
	v_mul_f32_e32 v84, v171, v171
	v_and_b32_e32 v173, 0xffff0000, v83
	v_lshlrev_b32_e32 v174, 16, v82
	v_mul_f32_e32 v82, v175, v175
	v_pk_fma_f32 v[238:239], v[170:171], v[170:171], v[84:85] op_sel_hi:[1,1,0]
	v_lshlrev_b32_e32 v172, 16, v83
	v_mul_f32_e32 v84, v173, v173
	v_pk_fma_f32 v[242:243], v[174:175], v[174:175], v[82:83] op_sel_hi:[1,1,0]
	v_and_b32_e32 v83, 0xffff0000, v81
	v_pk_fma_f32 v[240:241], v[172:173], v[172:173], v[84:85] op_sel_hi:[1,1,0]
	v_lshlrev_b32_e32 v82, 16, v81
	v_mul_f32_e32 v84, v83, v83
	v_lshlrev_b32_e32 v176, 16, v80
	v_mul_f32_e32 v80, v177, v177
	v_pk_fma_f32 v[244:245], v[82:83], v[82:83], v[84:85] op_sel_hi:[1,1,0]
	v_pk_fma_f32 v[80:81], v[176:177], v[176:177], v[80:81] op_sel_hi:[1,1,0]
	s_nop 0
	v_pk_add_f32 v[80:81], v[80:81], v[244:245]
	s_nop 0
	v_pk_add_f32 v[80:81], v[242:243], v[80:81]
	s_nop 0
	v_pk_add_f32 v[80:81], v[240:241], v[80:81]
	s_nop 0
	v_pk_add_f32 v[80:81], v[238:239], v[80:81]
	s_nop 0
	v_pk_add_f32 v[80:81], v[236:237], v[80:81]
	s_nop 0
	v_pk_add_f32 v[80:81], v[234:235], v[80:81]
	s_nop 0
	v_pk_add_f32 v[80:81], v[232:233], v[80:81]
	s_nop 0
	v_pk_add_f32 v[80:81], v[230:231], v[80:81]
	s_nop 0
	v_pk_add_f32 v[80:81], v[228:229], v[80:81]
	s_nop 0
	v_pk_add_f32 v[80:81], v[226:227], v[80:81]
	s_nop 0
	v_pk_add_f32 v[80:81], v[224:225], v[80:81]
	s_nop 0
	v_pk_add_f32 v[80:81], v[222:223], v[80:81]
	s_nop 0
	v_pk_add_f32 v[80:81], v[220:221], v[80:81]
	s_nop 0
	v_pk_add_f32 v[80:81], v[218:219], v[80:81]
	s_nop 0
	v_pk_add_f32 v[80:81], v[216:217], v[80:81]
	s_nop 0
	v_pk_add_f32 v[80:81], v[214:215], v[80:81]
	s_nop 0
	v_pk_add_f32 v[80:81], v[212:213], v[80:81]
	s_nop 0
	v_pk_add_f32 v[80:81], v[210:211], v[80:81]
	s_nop 0
	v_pk_add_f32 v[80:81], v[208:209], v[80:81]
	s_nop 0
	v_pk_add_f32 v[80:81], v[206:207], v[80:81]
	s_nop 0
	v_pk_add_f32 v[80:81], v[204:205], v[80:81]
	s_nop 0
	v_pk_add_f32 v[80:81], v[202:203], v[80:81]
	s_nop 0
	v_pk_add_f32 v[80:81], v[200:201], v[80:81]
	s_nop 0
	v_pk_add_f32 v[80:81], v[198:199], v[80:81]
	s_nop 0
	v_pk_add_f32 v[80:81], v[196:197], v[80:81]
	s_nop 0
	v_pk_add_f32 v[80:81], v[194:195], v[80:81] op_sel:[1,0] op_sel_hi:[0,1]
	v_pk_add_f32 v[80:81], v[194:195], v[80:81]
	s_nop 0
	v_pk_add_f32 v[80:81], v[192:193], v[80:81] op_sel:[1,0] op_sel_hi:[0,1]
	v_pk_add_f32 v[80:81], v[192:193], v[80:81]
	s_nop 0
	v_pk_add_f32 v[80:81], v[190:191], v[80:81] op_sel:[1,0] op_sel_hi:[0,1]
	v_pk_add_f32 v[80:81], v[190:191], v[80:81]
	s_nop 0
	v_mov_b32_e32 v81, v80
	s_nop 1
	v_permlane32_swap_b32_e32 v80, v81
	s_and_saveexec_b64 s[56:57], s[0:1]
	v_add_u32_e32 v84, 0, v187
	ds_write_b128 v84, v[112:115] offset:34816
	s_or_b64 exec, exec, s[56:57]
	v_add_f32_e32 v80, v80, v81
	v_fmamk_f32 v80, v80, 0x3c000000, v178
	v_mul_f32_e32 v81, 0x4b800000, v80
	v_cmp_gt_f32_e32 vcc, s68, v80
	v_mov_b32_e32 v123, v85
	v_mov_b32_e32 v109, v87
	v_cndmask_b32_e32 v80, v80, v81, vcc
	v_rsq_f32_e32 v80, v80
	v_mov_b32_e32 v111, v89
	v_mov_b32_e32 v127, v91
	v_mov_b32_e32 v125, v93
	v_mul_f32_e32 v81, 0x45800000, v80
	v_cndmask_b32_e32 v188, v80, v81, vcc
	v_pk_mul_f32 v[80:81], v[188:189], v[176:177] op_sel_hi:[0,1]
	s_waitcnt lgkmcnt(14)
	v_pk_mul_f32 v[76:77], v[76:77], v[80:81]
	v_mov_b32_e32 v107, v95
	v_cvt_pk_bf16_f32 v80, v76, v77
	v_pk_mul_f32 v[76:77], v[188:189], v[82:83] op_sel_hi:[0,1]
	v_pk_mul_f32 v[76:77], v[78:79], v[76:77]
	s_add_i32 s82, s3, s59
	v_cvt_pk_bf16_f32 v81, v76, v77
	v_pk_mul_f32 v[76:77], v[188:189], v[174:175] op_sel_hi:[0,1]
	v_pk_mul_f32 v[72:73], v[72:73], v[76:77]
	v_mul_lo_u32 v174, v119, s69
	v_cvt_pk_bf16_f32 v82, v72, v73
	v_pk_mul_f32 v[72:73], v[188:189], v[172:173] op_sel_hi:[0,1]
	v_pk_mul_f32 v[72:73], v[74:75], v[72:73]
	v_mul_lo_u32 v175, v189, s69
	v_cvt_pk_bf16_f32 v83, v72, v73
	v_pk_mul_f32 v[72:73], v[188:189], v[170:171] op_sel_hi:[0,1]
	s_waitcnt lgkmcnt(13)
	v_pk_mul_f32 v[68:69], v[68:69], v[72:73]
	s_add_i32 s15, s82, 16
	v_cvt_pk_bf16_f32 v84, v68, v69
	v_pk_mul_f32 v[68:69], v[188:189], v[168:169] op_sel_hi:[0,1]
	v_pk_mul_f32 v[68:69], v[70:71], v[68:69]
	v_lshlrev_b32_e32 v163, 3, v121
	v_cvt_pk_bf16_f32 v85, v68, v69
	v_pk_mul_f32 v[68:69], v[188:189], v[166:167] op_sel_hi:[0,1]
	s_waitcnt lgkmcnt(12)
	v_pk_mul_f32 v[64:65], v[64:65], v[68:69]
	s_add_i32 s82, s82, 47
	v_cvt_pk_bf16_f32 v86, v64, v65
	v_pk_mul_f32 v[64:65], v[188:189], v[164:165] op_sel_hi:[0,1]
	v_pk_mul_f32 v[64:65], v[66:67], v[64:65]
	s_mov_b32 s64, 1
	v_cvt_pk_bf16_f32 v87, v64, v65
	v_pk_mul_f32 v[64:65], v[188:189], v[158:159] op_sel_hi:[0,1]
	s_waitcnt lgkmcnt(11)
	v_pk_mul_f32 v[60:61], v[60:61], v[64:65]
	v_lshlrev_b32_e32 v159, 2, v121
	v_cvt_pk_bf16_f32 v88, v60, v61
	v_pk_mul_f32 v[60:61], v[188:189], v[152:153] op_sel_hi:[0,1]
	v_pk_mul_f32 v[60:61], v[62:63], v[60:61]
	v_add_u32_e32 v158, s15, v186
	v_cvt_pk_bf16_f32 v89, v60, v61
	v_pk_mul_f32 v[60:61], v[188:189], v[150:151] op_sel_hi:[0,1]
	s_waitcnt lgkmcnt(10)
	v_pk_mul_f32 v[56:57], v[56:57], v[60:61]
	v_mov_b32_e32 v60, v129
	v_cvt_pk_bf16_f32 v90, v56, v57
	v_pk_mul_f32 v[56:57], v[188:189], v[148:149] op_sel_hi:[0,1]
	v_pk_mul_f32 v[56:57], v[58:59], v[56:57]
	v_mov_b32_e32 v58, v129
	v_cvt_pk_bf16_f32 v91, v56, v57
	v_pk_mul_f32 v[56:57], v[188:189], v[146:147] op_sel_hi:[0,1]
	s_waitcnt lgkmcnt(9)
	v_pk_mul_f32 v[52:53], v[52:53], v[56:57]
	v_mov_b32_e32 v56, v129
	v_cvt_pk_bf16_f32 v92, v52, v53
	v_pk_mul_f32 v[52:53], v[188:189], v[144:145] op_sel_hi:[0,1]
	v_pk_mul_f32 v[52:53], v[54:55], v[52:53]
	v_mov_b32_e32 v54, v129
	v_cvt_pk_bf16_f32 v93, v52, v53
	v_pk_mul_f32 v[52:53], v[188:189], v[142:143] op_sel_hi:[0,1]
	s_waitcnt lgkmcnt(8)
	v_pk_mul_f32 v[48:49], v[48:49], v[52:53]
	v_mov_b32_e32 v52, v129
	v_cvt_pk_bf16_f32 v94, v48, v49
	v_pk_mul_f32 v[48:49], v[188:189], v[140:141] op_sel_hi:[0,1]
	v_pk_mul_f32 v[48:49], v[50:51], v[48:49]
	v_mov_b32_e32 v50, v129
	v_cvt_pk_bf16_f32 v95, v48, v49
	v_pk_mul_f32 v[48:49], v[188:189], v[96:97] op_sel_hi:[0,1]
	s_waitcnt lgkmcnt(7)
	v_pk_mul_f32 v[44:45], v[44:45], v[48:49]
	v_mov_b32_e32 v48, v129
	v_cvt_pk_bf16_f32 v96, v44, v45
	v_pk_mul_f32 v[44:45], v[188:189], v[138:139] op_sel_hi:[0,1]
	v_pk_mul_f32 v[44:45], v[46:47], v[44:45]
	v_mov_b32_e32 v49, v129
	v_cvt_pk_bf16_f32 v97, v44, v45
	v_pk_mul_f32 v[44:45], v[188:189], v[98:99] op_sel_hi:[0,1]
	s_waitcnt lgkmcnt(6)
	v_pk_mul_f32 v[40:41], v[40:41], v[44:45]
	v_mov_b32_e32 v51, v129
	v_cvt_pk_bf16_f32 v98, v40, v41
	v_pk_mul_f32 v[40:41], v[188:189], v[136:137] op_sel_hi:[0,1]
	v_pk_mul_f32 v[40:41], v[42:43], v[40:41]
	v_mov_b32_e32 v53, v129
	v_cvt_pk_bf16_f32 v99, v40, v41
	v_pk_mul_f32 v[40:41], v[188:189], v[100:101] op_sel_hi:[0,1]
	s_waitcnt lgkmcnt(5)
	v_pk_mul_f32 v[36:37], v[40:41], v[36:37]
	v_mov_b32_e32 v55, v129
	v_cvt_pk_bf16_f32 v100, v36, v37
	v_pk_mul_f32 v[36:37], v[188:189], v[134:135] op_sel_hi:[0,1]
	v_pk_mul_f32 v[36:37], v[36:37], v[38:39]
	v_mov_b32_e32 v57, v129
	v_cvt_pk_bf16_f32 v101, v36, v37
	v_pk_mul_f32 v[36:37], v[188:189], v[102:103] op_sel_hi:[0,1]
	s_waitcnt lgkmcnt(4)
	v_pk_mul_f32 v[32:33], v[36:37], v[32:33]
	v_mov_b32_e32 v59, v129
	v_cvt_pk_bf16_f32 v102, v32, v33
	v_pk_mul_f32 v[32:33], v[188:189], v[132:133] op_sel_hi:[0,1]
	v_pk_mul_f32 v[32:33], v[32:33], v[34:35]
	v_mov_b32_e32 v61, v129
	v_cvt_pk_bf16_f32 v103, v32, v33
	v_pk_mul_f32 v[32:33], v[188:189], v[104:105] op_sel_hi:[0,1]
	s_waitcnt lgkmcnt(3)
	v_pk_mul_f32 v[28:29], v[32:33], v[28:29]
	v_mov_b32_e32 v62, v129
	v_cvt_pk_bf16_f32 v104, v28, v29
	v_pk_mul_f32 v[28:29], v[188:189], v[130:131] op_sel_hi:[0,1]
	v_pk_mul_f32 v[28:29], v[28:29], v[30:31]
	v_mov_b32_e32 v63, v129
	v_cvt_pk_bf16_f32 v105, v28, v29
	v_pk_mul_f32 v[28:29], v[188:189], v[106:107] op_sel_hi:[0,1]
	s_waitcnt lgkmcnt(2)
	v_pk_mul_f32 v[24:25], v[28:29], v[24:25]
	v_mov_b64_e32 v[32:33], v[48:49]
	v_cvt_pk_bf16_f32 v106, v24, v25
	v_pk_mul_f32 v[24:25], v[188:189], v[126:127] op_sel_hi:[0,1]
	v_pk_mul_f32 v[24:25], v[24:25], v[26:27]
	v_mul_u32_u24_e32 v169, 0x110, v186
	v_cvt_pk_bf16_f32 v107, v24, v25
	v_pk_mul_f32 v[24:25], v[188:189], v[108:109] op_sel_hi:[0,1]
	s_waitcnt lgkmcnt(1)
	v_pk_mul_f32 v[20:21], v[24:25], v[20:21]
	v_mov_b32_e32 v155, v158
	v_cvt_pk_bf16_f32 v108, v20, v21
	v_pk_mul_f32 v[20:21], v[188:189], v[124:125] op_sel_hi:[0,1]
	v_pk_mul_f32 v[20:21], v[20:21], v[22:23]
	v_lshl_add_u64 v[164:165], v[116:117], 2, s[4:5]
	v_cvt_pk_bf16_f32 v109, v20, v21
	v_pk_mul_f32 v[20:21], v[188:189], v[110:111] op_sel_hi:[0,1]
	s_waitcnt lgkmcnt(0)
	v_pk_mul_f32 v[16:17], v[20:21], v[16:17]
	v_add_u32_e32 v20, 0, v128
	v_cvt_pk_bf16_f32 v110, v16, v17
	v_pk_mul_f32 v[16:17], v[188:189], v[122:123] op_sel_hi:[0,1]
	v_pk_mul_f32 v[16:17], v[16:17], v[18:19]
	v_and_b32_e32 v19, 16, v154
	v_cvt_pk_bf16_f32 v111, v16, v17
	v_lshlrev_b32_e32 v16, 16, v12
	v_and_b32_e32 v17, 0xffff0000, v12
	v_pk_mul_f32 v[16:17], v[120:121], v[16:17] op_sel_hi:[0,1]
	v_cvt_pk_bf16_f32 v12, v16, v17
	v_lshlrev_b32_e32 v16, 16, v13
	v_and_b32_e32 v17, 0xffff0000, v13
	v_pk_mul_f32 v[16:17], v[120:121], v[16:17] op_sel_hi:[0,1]
	v_cvt_pk_bf16_f32 v13, v16, v17
	v_lshlrev_b32_e32 v16, 16, v14
	v_and_b32_e32 v17, 0xffff0000, v14
	v_pk_mul_f32 v[16:17], v[120:121], v[16:17] op_sel_hi:[0,1]
	v_cvt_pk_bf16_f32 v14, v16, v17
	v_lshlrev_b32_e32 v16, 16, v15
	v_and_b32_e32 v17, 0xffff0000, v15
	v_pk_mul_f32 v[16:17], v[120:121], v[16:17] op_sel_hi:[0,1]
	v_cvt_pk_bf16_f32 v15, v16, v17
	v_add_u32_e32 v16, v20, v174
	ds_write_b128 v16, v[12:15]
	ds_write_b128 v248, v[8:11] offset:17408
	v_lshlrev_b32_e32 v8, 16, v4
	v_and_b32_e32 v9, 0xffff0000, v4
	v_pk_mul_f32 v[8:9], v[118:119], v[8:9] op_sel_hi:[0,1]
	v_cvt_pk_bf16_f32 v4, v8, v9
	v_lshlrev_b32_e32 v8, 16, v5
	v_and_b32_e32 v9, 0xffff0000, v5
	v_pk_mul_f32 v[8:9], v[118:119], v[8:9] op_sel_hi:[0,1]
	v_cvt_pk_bf16_f32 v5, v8, v9
	v_lshlrev_b32_e32 v8, 16, v6
	v_and_b32_e32 v9, 0xffff0000, v6
	v_pk_mul_f32 v[8:9], v[118:119], v[8:9] op_sel_hi:[0,1]
	v_cvt_pk_bf16_f32 v6, v8, v9
	v_lshlrev_b32_e32 v8, 16, v7
	v_and_b32_e32 v9, 0xffff0000, v7
	v_pk_mul_f32 v[8:9], v[118:119], v[8:9] op_sel_hi:[0,1]
	v_cvt_pk_bf16_f32 v7, v8, v9
	v_add_u32_e32 v8, v20, v175
	ds_write_b128 v8, v[4:7]
	ds_write_b128 v248, v[0:3] offset:25600
	v_lshlrev_b32_e32 v1, 2, v185
	v_lshrrev_b32_e32 v18, 2, v154
	v_and_or_b32 v1, v1, 12, v19
	v_and_or_b32 v0, v18, 3, v159
	v_lshlrev_b32_e32 v177, 1, v1
	v_or_b32_e32 v1, 32, v185
	v_mul_u32_u24_e32 v176, 0x110, v1
	v_mul_u32_u24_e32 v188, 0x110, v0
	v_mov_b64_e32 v[16:17], v[48:49]
	v_mov_b64_e32 v[0:1], v[48:49]
	s_and_b32 s12, s58, 0xfc0
	v_subrev_u32_e32 v189, 64, v189
	v_subrev_u32_e32 v190, 64, v119
	v_mov_b32_e32 v167, 0
	v_mov_b32_e32 v192, 0xff800000
	v_mov_b64_e32 v[34:35], v[50:51]
	v_mov_b64_e32 v[36:37], v[52:53]
	v_mov_b64_e32 v[38:39], v[54:55]
	v_mov_b64_e32 v[40:41], v[56:57]
	v_mov_b64_e32 v[42:43], v[58:59]
	v_mov_b64_e32 v[44:45], v[60:61]
	v_mov_b64_e32 v[46:47], v[62:63]
	v_mov_b64_e32 v[18:19], v[50:51]
	v_mov_b64_e32 v[20:21], v[52:53]
	v_mov_b64_e32 v[22:23], v[54:55]
	v_mov_b64_e32 v[24:25], v[56:57]
	v_mov_b64_e32 v[26:27], v[58:59]
	v_mov_b64_e32 v[28:29], v[60:61]
	v_mov_b64_e32 v[30:31], v[62:63]
	v_mov_b64_e32 v[2:3], v[50:51]
	v_mov_b64_e32 v[4:5], v[52:53]
	v_mov_b64_e32 v[6:7], v[54:55]
	v_mov_b64_e32 v[8:9], v[56:57]
	v_mov_b64_e32 v[10:11], v[58:59]
	v_mov_b64_e32 v[12:13], v[60:61]
	v_mov_b64_e32 v[14:15], v[62:63]
	s_and_saveexec_b64 s[4:5], s[0:1]
	s_cbranch_execz .Llde_p
	v_lshl_add_u64 v[64:65], s[12:13], 2, v[164:165]
	global_load_dwordx4 v[112:115], v[64:65], off offset:-256
.Llde_p:
	s_or_b64 exec, exec, s[4:5]
	v_add_u32_e32 v65, s12, v190
	v_mov_b32_e32 v70, s33
	v_cmp_lt_i32_e32 vcc, 15, v65
	v_min_i32_e32 v64, 0x80f, v65
	v_cndmask_b32_e32 v65, v179, v70, vcc
	v_add_u32_e32 v66, v65, v64
	v_ashrrev_i32_e32 v67, 31, v66
	v_lshlrev_b64 v[66:67], 14, v[66:67]
	v_lshl_add_u64 v[66:67], v[160:161], 0, v[66:67]
	v_add_co_u32_e32 v68, vcc, s65, v66
	v_ashrrev_i32_e32 v65, 31, v64
	s_nop 0
	v_addc_co_u32_e32 v69, vcc, 0, v67, vcc
	v_add_co_u32_e32 v66, vcc, s63, v66
	v_lshl_add_u64 v[64:65], v[64:65], 2, s[54:55]
	s_nop 0
	v_addc_co_u32_e32 v67, vcc, 0, v67, vcc
	global_load_dwordx4 v[130:133], v[68:69], off offset:2048
	global_load_dwordx4 v[116:119], v[66:67], off
	v_add_u32_e32 v67, s12, v189
	v_cmp_lt_i32_e32 vcc, 15, v67
	v_min_i32_e32 v66, 0x80f, v67
	v_cndmask_b32_e32 v67, v179, v70, vcc
	v_add_u32_e32 v68, v67, v66
	v_ashrrev_i32_e32 v69, 31, v68
	v_lshlrev_b64 v[68:69], 14, v[68:69]
	v_lshl_add_u64 v[68:69], v[160:161], 0, v[68:69]
	v_add_co_u32_e32 v70, vcc, 0x2000, v68
	v_ashrrev_i32_e32 v67, 31, v66
	s_nop 0
	v_addc_co_u32_e32 v71, vcc, 0, v69, vcc
	global_load_dword v168, v[64:65], off
	global_load_dwordx4 v[120:123], v[70:71], off offset:2048
	v_add_co_u32_e32 v64, vcc, 0x3000, v68
	v_lshl_add_u64 v[66:67], v[66:67], 2, s[54:55]
	s_nop 0
	v_addc_co_u32_e32 v65, vcc, 0, v69, vcc
	global_load_dwordx4 v[124:127], v[64:65], off
	global_load_dword v166, v[66:67], off
	s_waitcnt lgkmcnt(0)
	s_barrier
	s_branch .LBB0_507
.LBB0_506:
	s_or_b64 exec, exec, s[4:5]
	s_waitcnt vmcnt(5)
	v_lshlrev_b32_e32 v64, 16, v130
	v_and_b32_e32 v65, 0xffff0000, v130
	v_lshlrev_b32_e32 v66, 16, v131
	v_and_b32_e32 v67, 0xffff0000, v131
	s_waitcnt vmcnt(3)
	v_pk_mul_f32 v[64:65], v[168:169], v[64:65] op_sel_hi:[0,1]
	v_pk_mul_f32 v[66:67], v[168:169], v[66:67] op_sel_hi:[0,1]
	v_cvt_pk_bf16_f32 v64, v64, v65
	v_cvt_pk_bf16_f32 v65, v66, v67
	v_lshlrev_b32_e32 v66, 16, v132
	v_and_b32_e32 v67, 0xffff0000, v132
	v_lshlrev_b32_e32 v68, 16, v133
	v_and_b32_e32 v69, 0xffff0000, v133
	v_add_u32_e32 v70, s56, v128
	v_pk_mul_f32 v[66:67], v[168:169], v[66:67] op_sel_hi:[0,1]
	v_pk_mul_f32 v[68:69], v[168:169], v[68:69] op_sel_hi:[0,1]
	v_cvt_pk_bf16_f32 v66, v66, v67
	v_cvt_pk_bf16_f32 v67, v68, v69
	v_add_u32_e32 v68, v70, v174
	ds_write_b128 v68, v[64:67]
	v_add_u32_e32 v71, s56, v248
	ds_write_b128 v71, v[116:119] offset:17408
	s_waitcnt vmcnt(2)
	v_lshlrev_b32_e32 v64, 16, v120
	v_and_b32_e32 v65, 0xffff0000, v120
	v_lshlrev_b32_e32 v66, 16, v121
	v_and_b32_e32 v67, 0xffff0000, v121
	s_waitcnt vmcnt(0)
	v_pk_mul_f32 v[64:65], v[166:167], v[64:65] op_sel_hi:[0,1]
	v_pk_mul_f32 v[66:67], v[166:167], v[66:67] op_sel_hi:[0,1]
	v_cvt_pk_bf16_f32 v64, v64, v65
	v_cvt_pk_bf16_f32 v65, v66, v67
	v_lshlrev_b32_e32 v66, 16, v122
	v_and_b32_e32 v67, 0xffff0000, v122
	v_lshlrev_b32_e32 v68, 16, v123
	v_and_b32_e32 v69, 0xffff0000, v123
	v_pk_mul_f32 v[66:67], v[166:167], v[66:67] op_sel_hi:[0,1]
	v_pk_mul_f32 v[68:69], v[166:167], v[68:69] op_sel_hi:[0,1]
	s_sub_i32 s12, s12, 64
	s_add_i32 s64, s64, 1
	v_cvt_pk_bf16_f32 v66, v66, v67
	v_cvt_pk_bf16_f32 v67, v68, v69
	v_add_u32_e32 v68, v70, v175
	s_cmp_eq_u32 s12, 0
	ds_write_b128 v68, v[64:67]
	ds_write_b128 v71, v[124:127] offset:25600
	s_cbranch_scc1 .Lld_skip
	s_and_saveexec_b64 s[4:5], s[0:1]
	s_cbranch_execz .Llde_b
	v_lshl_add_u64 v[64:65], s[12:13], 2, v[164:165]
	global_load_dwordx4 v[112:115], v[64:65], off offset:-256
.Llde_b:
	s_or_b64 exec, exec, s[4:5]
	v_add_u32_e32 v65, s12, v190
	v_mov_b32_e32 v70, s33
	v_cmp_lt_i32_e32 vcc, 15, v65
	v_min_i32_e32 v64, 0x80f, v65
	v_cndmask_b32_e32 v65, v179, v70, vcc
	v_add_u32_e32 v66, v65, v64
	v_ashrrev_i32_e32 v67, 31, v66
	v_lshlrev_b64 v[66:67], 14, v[66:67]
	v_lshl_add_u64 v[66:67], v[160:161], 0, v[66:67]
	v_add_co_u32_e32 v68, vcc, s65, v66
	v_ashrrev_i32_e32 v65, 31, v64
	s_nop 0
	v_addc_co_u32_e32 v69, vcc, 0, v67, vcc
	v_add_co_u32_e32 v66, vcc, s63, v66
	v_lshl_add_u64 v[64:65], v[64:65], 2, s[54:55]
	s_nop 0
	v_addc_co_u32_e32 v67, vcc, 0, v67, vcc
	global_load_dwordx4 v[130:133], v[68:69], off offset:2048
	global_load_dwordx4 v[116:119], v[66:67], off
	v_add_u32_e32 v67, s12, v189
	v_cmp_lt_i32_e32 vcc, 15, v67
	v_min_i32_e32 v66, 0x80f, v67
	v_cndmask_b32_e32 v67, v179, v70, vcc
	v_add_u32_e32 v68, v67, v66
	v_ashrrev_i32_e32 v69, 31, v68
	v_lshlrev_b64 v[68:69], 14, v[68:69]
	v_lshl_add_u64 v[68:69], v[160:161], 0, v[68:69]
	v_add_co_u32_e32 v70, vcc, 0x2000, v68
	v_ashrrev_i32_e32 v67, 31, v66
	s_nop 0
	v_addc_co_u32_e32 v71, vcc, 0, v69, vcc
	global_load_dword v168, v[64:65], off
	global_load_dwordx4 v[120:123], v[70:71], off offset:2048
	v_add_co_u32_e32 v64, vcc, 0x3000, v68
	v_lshl_add_u64 v[66:67], v[66:67], 2, s[54:55]
	s_nop 0
	v_addc_co_u32_e32 v65, vcc, 0, v69, vcc
	global_load_dwordx4 v[124:127], v[64:65], off
	global_load_dword v166, v[66:67], off
.Lld_skip:
	s_waitcnt lgkmcnt(0)
	s_barrier
	s_cmp_eq_u32 s12, 0
	s_cbranch_scc1 .LBB0_568
.LBB0_507:
	s_and_b32 s89, 1, s64
	s_cselect_b32 s4, 0, 0x8a00
	s_add_i32 s4, s4, 0
	v_add_u32_e32 v193, s4, v162
	v_add_u32_e32 v64, s4, v177
	v_add_u32_e32 v191, s4, v247
	s_add_i32 s5, s12, 63
	s_cmp_le_i32 s5, s15
	s_cbranch_scc1 .Lswp
	s_add_i32 s4, s12, 32
	s_cmp_gt_i32 s4, s82
	s_cbranch_scc1 .LBB0_530
	v_add_u32_e32 v68, v193, v176
	ds_read_b128 v[64:67], v68
	ds_read_b128 v[134:137], v68 offset:32
	ds_read_b128 v[138:141], v68 offset:64
	ds_read_b128 v[142:145], v68 offset:96
	ds_read_b128 v[150:153], v68 offset:128
	ds_read_b128 v[170:173], v68 offset:160
	ds_read_b128 v[194:197], v68 offset:192
	ds_read_b128 v[198:201], v68 offset:224
	s_waitcnt lgkmcnt(7)
	v_mfma_f32_32x32x16_bf16 v[64:79], v[64:67], v[80:83], 0
	s_add_i32 s4, s12, 63
	s_cmp_le_i32 s4, s15
	s_cselect_b64 s[56:57], -1, 0
	s_cmp_gt_i32 s4, s15
	s_mov_b64 s[4:5], -1
	s_waitcnt lgkmcnt(6)
	v_mfma_f32_32x32x16_bf16 v[64:79], v[134:137], v[84:87], v[64:79]
	s_waitcnt lgkmcnt(5)
	v_mfma_f32_32x32x16_bf16 v[64:79], v[138:141], v[88:91], v[64:79]
	s_waitcnt lgkmcnt(4)
	v_mfma_f32_32x32x16_bf16 v[64:79], v[142:145], v[92:95], v[64:79]
	ds_read_b64_tr_b16 v[146:147], v191 offset:25600
	ds_read_b64_tr_b16 v[148:149], v191 offset:27648
	ds_read_b64_tr_b16 v[142:143], v191 offset:29696
	ds_read_b64_tr_b16 v[144:145], v191 offset:31744
	ds_read_b64_tr_b16 v[138:139], v191 offset:26112
	ds_read_b64_tr_b16 v[140:141], v191 offset:28160
	ds_read_b64_tr_b16 v[134:135], v191 offset:30208
	ds_read_b64_tr_b16 v[136:137], v191 offset:32256
	s_waitcnt lgkmcnt(11)
	v_mfma_f32_32x32x16_bf16 v[64:79], v[150:153], v[96:99], v[64:79]
	ds_read_b128 v[150:153], v193 offset:34944
	s_waitcnt lgkmcnt(11)
	v_mfma_f32_32x32x16_bf16 v[64:79], v[170:173], v[100:103], v[64:79]
	s_waitcnt lgkmcnt(0)
	v_xor_b32_e32 v173, 0x80000000, v152
	v_mfma_f32_32x32x16_bf16 v[64:79], v[194:197], v[104:107], v[64:79]
	v_mfma_f32_32x32x16_bf16 v[64:79], v[198:201], v[108:111], v[64:79]
	s_nop 11
	v_sub_f32_e32 v195, v64, v150
	s_cbranch_scc1 .LBB0_512
	v_mov_b32_e32 v170, v65
	v_mov_b32_e32 v171, v66
	v_xor_b32_e32 v172, 0x80000000, v151
	v_pk_add_f32 v[170:171], v[170:171], v[172:173]
	v_sub_f32_e32 v172, v67, v153
	v_max3_f32 v64, v195, s87, v170
	v_max3_f32 v196, v64, v171, v172
	ds_read_b128 v[64:67], v193 offset:34976
	s_waitcnt lgkmcnt(0)
	v_xor_b32_e32 v67, 0x80000000, v67
	v_xor_b32_e32 v66, 0x80000000, v66
	v_pk_add_f32 v[150:151], v[68:69], v[64:65] neg_lo:[0,1] neg_hi:[0,1]
	v_pk_add_f32 v[152:153], v[70:71], v[66:67]
	v_max3_f32 v173, v196, v150, v151
	v_max3_f32 v173, v173, v152, v153
	ds_read_b128 v[64:67], v193 offset:35008
	s_waitcnt lgkmcnt(0)
	v_xor_b32_e32 v67, 0x80000000, v67
	v_xor_b32_e32 v66, 0x80000000, v66
	v_pk_add_f32 v[68:69], v[72:73], v[64:65] neg_lo:[0,1] neg_hi:[0,1]
	v_pk_add_f32 v[70:71], v[74:75], v[66:67]
	v_max3_f32 v196, v173, v68, v69
	v_max3_f32 v196, v196, v70, v71
	ds_read_b128 v[64:67], v193 offset:35040
	s_waitcnt lgkmcnt(0)
	v_xor_b32_e32 v75, 0x80000000, v67
	v_xor_b32_e32 v74, 0x80000000, v66
	v_pk_add_f32 v[72:73], v[76:77], v[64:65] neg_lo:[0,1] neg_hi:[0,1]
	v_pk_add_f32 v[66:67], v[78:79], v[74:75]
	v_max3_f32 v173, v196, v72, v73
	v_max3_f32 v173, v173, v66, v67

.LBB0_550:
	s_cmp_eq_u32 s89, 1
	s_cselect_b32 s4, 0x8a00, 0
	s_add_i32 s56, s4, 0
	s_and_saveexec_b64 s[4:5], s[0:1]
	s_cbranch_execz .LBB0_506
	v_add_u32_e32 v64, s56, v187
	s_waitcnt vmcnt(6)
	ds_write_b128 v64, v[112:115] offset:34816
	v_xor_b32_e32 v66, 0x80000000, v112
	v_xor_b32_e32 v67, 0x80000000, v113
	v_xor_b32_e32 v68, 0x80000000, v114
	v_xor_b32_e32 v69, 0x80000000, v115
	ds_write_b128 v64, v[66:69] offset:35072
	s_branch .LBB0_506

.Lswp:
	v_add_u32_e32 v195, v193, v176
	v_add_u32_e32 v249, v193, v169
	ds_read_b128 v[64:67], v193 offset:35200
	ds_read_b128 v[68:71], v193 offset:35232
	ds_read_b128 v[72:75], v193 offset:35264
	ds_read_b128 v[76:79], v193 offset:35296
	ds_read_b128 v[220:223], v195 offset:0
	ds_read_b128 v[224:227], v195 offset:32
	ds_read_b128 v[228:231], v195 offset:64
	ds_read_b128 v[232:235], v195 offset:96
	ds_read_b128 v[236:239], v195 offset:128
	ds_read_b128 v[240:243], v195 offset:160
	ds_read_b128 v[250:253], v195 offset:192
	ds_read_b128 v[134:137], v195 offset:224
	s_waitcnt lgkmcnt(7)
	v_mfma_f32_32x32x16_bf16 v[64:79], v[220:223], v[80:83], v[64:79]
	ds_read_b128 v[138:141], v249 offset:0
	ds_read_b128 v[142:145], v249 offset:32
	s_waitcnt lgkmcnt(8)
	v_mfma_f32_32x32x16_bf16 v[64:79], v[224:227], v[84:87], v[64:79]
	ds_read_b128 v[146:149], v249 offset:64
	ds_read_b128 v[150:153], v249 offset:96
	s_waitcnt lgkmcnt(9)
	v_mfma_f32_32x32x16_bf16 v[64:79], v[228:231], v[88:91], v[64:79]
	ds_read_b128 v[220:223], v249 offset:128
	ds_read_b128 v[224:227], v249 offset:160
	s_waitcnt lgkmcnt(10)
	v_mfma_f32_32x32x16_bf16 v[64:79], v[232:235], v[92:95], v[64:79]
	ds_read_b128 v[228:231], v249 offset:192
	ds_read_b128 v[232:235], v249 offset:224
	s_waitcnt lgkmcnt(11)
	v_mfma_f32_32x32x16_bf16 v[64:79], v[236:239], v[96:99], v[64:79]
	ds_read_b128 v[204:207], v193 offset:35072
	ds_read_b128 v[208:211], v193 offset:35104
	s_waitcnt lgkmcnt(12)
	v_mfma_f32_32x32x16_bf16 v[64:79], v[240:243], v[100:103], v[64:79]
	ds_read_b128 v[212:215], v193 offset:35136
	ds_read_b128 v[216:219], v193 offset:35168
	s_waitcnt lgkmcnt(13)
	v_mfma_f32_32x32x16_bf16 v[64:79], v[250:253], v[104:107], v[64:79]
	ds_read_b64_tr_b16 v[240:241], v191 offset:25600
	ds_read_b64_tr_b16 v[242:243], v191 offset:27648
	s_waitcnt lgkmcnt(14)
	v_mfma_f32_32x32x16_bf16 v[64:79], v[134:137], v[108:111], v[64:79]
	ds_read_b64_tr_b16 v[250:251], v191 offset:26112
	s_waitcnt lgkmcnt(14)
	ds_read_b64_tr_b16 v[252:253], v191 offset:28160
	s_waitcnt lgkmcnt(4)
	v_mfma_f32_32x32x16_bf16 v[204:219], v[138:141], v[80:83], v[204:219]
	ds_read_b64_tr_b16 v[134:135], v191 offset:26624
	ds_read_b64_tr_b16 v[136:137], v191 offset:28672
	v_mfma_f32_32x32x16_bf16 v[204:219], v[142:145], v[84:87], v[204:219]
	ds_read_b64_tr_b16 v[138:139], v191 offset:27136
	ds_read_b64_tr_b16 v[140:141], v191 offset:29184
	ds_read_b64_tr_b16 v[142:143], v191 offset:29696
	ds_read_b64_tr_b16 v[144:145], v191 offset:31744
	s_nop 1
	v_max3_f32 v254, v64, s87, v65
	v_max3_f32 v254, v254, v66, v67
	v_max3_f32 v254, v254, v68, v69
	v_max3_f32 v254, v254, v70, v71
	v_max3_f32 v254, v254, v72, v73
	v_max3_f32 v254, v254, v74, v75
	v_max3_f32 v254, v254, v76, v77
	v_max3_f32 v254, v254, v78, v79
	v_mfma_f32_32x32x16_bf16 v[204:219], v[146:149], v[88:91], v[204:219]
	ds_read_b64_tr_b16 v[146:147], v191 offset:30208
	ds_read_b64_tr_b16 v[148:149], v191 offset:32256
	v_mov_b32_e32 v255, v254
	s_nop 1
	v_permlane32_swap_b32_e32 v254, v255
	v_max_f32_e32 v255, v255, v255
	v_max_f32_e32 v254, v254, v254
	v_max_f32_e32 v255, v254, v255
	v_max_f32_e32 v249, v192, v192
	v_max_f32_e32 v194, v249, v255
	v_cmp_neq_f32_e64 s[4:5], s87, v194
	v_mfma_f32_32x32x16_bf16 v[204:219], v[150:153], v[92:95], v[204:219]
	ds_read_b64_tr_b16 v[150:151], v191 offset:30720
	ds_read_b64_tr_b16 v[152:153], v191 offset:32768
	v_cmp_gt_f32_e32 vcc, v255, v192
	s_nop 0
	v_cndmask_b32_e64 v244, 0, v194, s[4:5]
	s_cbranch_vccnz .LswpA_resc
.LswpA_back:
	v_pk_add_f32 v[64:65], v[64:65], v[244:245] op_sel_hi:[1,0] neg_lo:[0,1] neg_hi:[0,1]
	v_pk_add_f32 v[66:67], v[66:67], v[244:245] op_sel_hi:[1,0] neg_lo:[0,1] neg_hi:[0,1]
	v_pk_add_f32 v[68:69], v[68:69], v[244:245] op_sel_hi:[1,0] neg_lo:[0,1] neg_hi:[0,1]
	v_pk_add_f32 v[70:71], v[70:71], v[244:245] op_sel_hi:[1,0] neg_lo:[0,1] neg_hi:[0,1]
	v_pk_add_f32 v[72:73], v[72:73], v[244:245] op_sel_hi:[1,0] neg_lo:[0,1] neg_hi:[0,1]
	v_pk_add_f32 v[74:75], v[74:75], v[244:245] op_sel_hi:[1,0] neg_lo:[0,1] neg_hi:[0,1]
	v_pk_add_f32 v[76:77], v[76:77], v[244:245] op_sel_hi:[1,0] neg_lo:[0,1] neg_hi:[0,1]
	v_pk_add_f32 v[78:79], v[78:79], v[244:245] op_sel_hi:[1,0] neg_lo:[0,1] neg_hi:[0,1]
	v_exp_f32_e32 v64, v64
	v_mfma_f32_32x32x16_bf16 v[204:219], v[220:223], v[96:99], v[204:219]
	ds_read_b64_tr_b16 v[220:221], v191 offset:31232
	s_waitcnt lgkmcnt(14)
	ds_read_b64_tr_b16 v[222:223], v191 offset:33280
	v_exp_f32_e32 v65, v65
	v_exp_f32_e32 v66, v66
	v_exp_f32_e32 v67, v67
	v_exp_f32_e32 v68, v68
	v_exp_f32_e32 v69, v69
	v_exp_f32_e32 v70, v70
	v_exp_f32_e32 v71, v71
	v_cvt_pk_bf16_f32 v200, v64, v65
	v_mfma_f32_32x32x16_bf16 v[204:219], v[224:227], v[100:103], v[204:219]
	v_cvt_pk_bf16_f32 v201, v66, v67
	v_cvt_pk_bf16_f32 v202, v68, v69
	v_cvt_pk_bf16_f32 v203, v70, v71
	v_exp_f32_e32 v72, v72
	v_mfma_f32_32x32x16_bf16 v[204:219], v[228:231], v[104:107], v[204:219]
	v_exp_f32_e32 v73, v73
	v_exp_f32_e32 v74, v74
	v_exp_f32_e32 v75, v75
	v_exp_f32_e32 v76, v76
	v_mfma_f32_32x32x16_bf16 v[204:219], v[232:235], v[108:111], v[204:219]
	s_waitcnt lgkmcnt(14)
	ds_read_b64_tr_b16 v[232:233], v191 offset:17408
	s_waitcnt lgkmcnt(14)
	ds_read_b64_tr_b16 v[234:235], v191 offset:19456
	v_exp_f32_e32 v77, v77
	v_exp_f32_e32 v78, v78
	v_exp_f32_e32 v79, v79
	v_cvt_pk_bf16_f32 v236, v72, v73
	v_cvt_pk_bf16_f32 v237, v74, v75
	v_cvt_pk_bf16_f32 v238, v76, v77
	v_cvt_pk_bf16_f32 v239, v78, v79
	v_mfma_f32_32x32x16_bf16 v[48:63], v[240:243], v[200:203], v[48:63]
	v_pk_add_f32 v[254:255], v[64:65], v[66:67]
	v_pk_add_f32 v[254:255], v[68:69], v[254:255]
	v_pk_add_f32 v[254:255], v[70:71], v[254:255]
	v_pk_add_f32 v[254:255], v[72:73], v[254:255]
	v_pk_add_f32 v[254:255], v[74:75], v[254:255]
	v_pk_add_f32 v[254:255], v[76:77], v[254:255]
	v_pk_add_f32 v[254:255], v[78:79], v[254:255]
	v_add_f32_e32 v195, v254, v255
	s_waitcnt lgkmcnt(14)
	v_mfma_f32_32x32x16_bf16 v[32:47], v[250:253], v[200:203], v[32:47]
	v_add_f32_e32 v167, v195, v167
	s_waitcnt lgkmcnt(12)
	v_mfma_f32_32x32x16_bf16 v[16:31], v[134:137], v[200:203], v[16:31]
	ds_read_b64_tr_b16 v[64:65], v191 offset:17920
	ds_read_b64_tr_b16 v[66:67], v191 offset:19968
	ds_read_b64_tr_b16 v[68:69], v191 offset:18432
	s_waitcnt lgkmcnt(14)
	ds_read_b64_tr_b16 v[70:71], v191 offset:20480
	s_waitcnt lgkmcnt(14)
	ds_read_b64_tr_b16 v[72:73], v191 offset:18944
	s_waitcnt lgkmcnt(14)
	ds_read_b64_tr_b16 v[74:75], v191 offset:20992
	v_max3_f32 v254, v204, s87, v205
	v_max3_f32 v254, v254, v206, v207
	v_max3_f32 v254, v254, v208, v209
	v_max3_f32 v254, v254, v210, v211
	v_max3_f32 v254, v254, v212, v213
	v_max3_f32 v254, v254, v214, v215
	v_max3_f32 v254, v254, v216, v217
	v_max3_f32 v254, v254, v218, v219
	v_mfma_f32_32x32x16_bf16 v[0:15], v[138:141], v[200:203], v[0:15]
	s_waitcnt lgkmcnt(14)
	ds_read_b64_tr_b16 v[76:77], v191 offset:21504
	s_waitcnt lgkmcnt(14)
	ds_read_b64_tr_b16 v[78:79], v191 offset:23552
	v_mov_b32_e32 v255, v254
	s_nop 1
	v_permlane32_swap_b32_e32 v254, v255
	v_max_f32_e32 v255, v255, v255
	v_max_f32_e32 v254, v254, v254
	v_max_f32_e32 v255, v254, v255
	v_max_f32_e32 v249, v194, v194
	v_max_f32_e32 v192, v249, v255
	v_cmp_neq_f32_e64 s[4:5], s87, v192
	v_mfma_f32_32x32x16_bf16 v[48:63], v[142:145], v[236:239], v[48:63]
	s_waitcnt lgkmcnt(14)
	ds_read_b64_tr_b16 v[240:241], v191 offset:22016
	s_waitcnt lgkmcnt(14)
	ds_read_b64_tr_b16 v[242:243], v191 offset:24064
	v_cmp_gt_f32_e64 s[56:57], v255, v194
	s_nop 0
	v_cndmask_b32_e64 v244, 0, v192, s[4:5]
	v_pk_add_f32 v[204:205], v[204:205], v[244:245] op_sel_hi:[1,0] neg_lo:[0,1] neg_hi:[0,1]
	v_pk_add_f32 v[206:207], v[206:207], v[244:245] op_sel_hi:[1,0] neg_lo:[0,1] neg_hi:[0,1]
	v_pk_add_f32 v[208:209], v[208:209], v[244:245] op_sel_hi:[1,0] neg_lo:[0,1] neg_hi:[0,1]
	v_pk_add_f32 v[210:211], v[210:211], v[244:245] op_sel_hi:[1,0] neg_lo:[0,1] neg_hi:[0,1]
	v_pk_add_f32 v[212:213], v[212:213], v[244:245] op_sel_hi:[1,0] neg_lo:[0,1] neg_hi:[0,1]
	v_pk_add_f32 v[214:215], v[214:215], v[244:245] op_sel_hi:[1,0] neg_lo:[0,1] neg_hi:[0,1]
	v_pk_add_f32 v[216:217], v[216:217], v[244:245] op_sel_hi:[1,0] neg_lo:[0,1] neg_hi:[0,1]
	v_pk_add_f32 v[218:219], v[218:219], v[244:245] op_sel_hi:[1,0] neg_lo:[0,1] neg_hi:[0,1]
	v_exp_f32_e32 v204, v204
	v_mfma_f32_32x32x16_bf16 v[32:47], v[146:149], v[236:239], v[32:47]
	s_waitcnt lgkmcnt(14)
	ds_read_b64_tr_b16 v[250:251], v191 offset:22528
	s_waitcnt lgkmcnt(14)
	ds_read_b64_tr_b16 v[252:253], v191 offset:24576
	v_exp_f32_e32 v205, v205
	v_exp_f32_e32 v206, v206
	v_exp_f32_e32 v207, v207
	v_exp_f32_e32 v208, v208
	v_exp_f32_e32 v209, v209
	v_exp_f32_e32 v210, v210
	v_exp_f32_e32 v211, v211
	v_cvt_pk_bf16_f32 v170, v204, v205
	v_mfma_f32_32x32x16_bf16 v[16:31], v[150:153], v[236:239], v[16:31]
	s_waitcnt lgkmcnt(14)
	ds_read_b64_tr_b16 v[134:135], v191 offset:23040
	s_waitcnt lgkmcnt(14)
	ds_read_b64_tr_b16 v[136:137], v191 offset:25088
	v_cvt_pk_bf16_f32 v171, v206, v207
	v_cvt_pk_bf16_f32 v172, v208, v209
	v_cvt_pk_bf16_f32 v173, v210, v211
	v_exp_f32_e32 v212, v212
	v_exp_f32_e32 v213, v213
	v_exp_f32_e32 v214, v214
	v_exp_f32_e32 v215, v215
	v_exp_f32_e32 v216, v216
	v_mfma_f32_32x32x16_bf16 v[0:15], v[220:223], v[236:239], v[0:15]
	v_exp_f32_e32 v217, v217
	v_exp_f32_e32 v218, v218
	v_exp_f32_e32 v219, v219
	v_cvt_pk_bf16_f32 v196, v212, v213
	v_cvt_pk_bf16_f32 v197, v214, v215
	v_cvt_pk_bf16_f32 v198, v216, v217
	v_cvt_pk_bf16_f32 v199, v218, v219
	s_cmp_lg_u64 s[56:57], 0
	s_cbranch_scc1 .LswpB_resc
.LswpB_back:
	s_waitcnt lgkmcnt(14)
	v_mfma_f32_32x32x16_bf16 v[48:63], v[232:235], v[170:173], v[48:63]
	v_pk_add_f32 v[254:255], v[204:205], v[206:207]
	v_pk_add_f32 v[254:255], v[208:209], v[254:255]
	v_pk_add_f32 v[254:255], v[210:211], v[254:255]
	s_waitcnt lgkmcnt(12)
	v_mfma_f32_32x32x16_bf16 v[32:47], v[64:67], v[170:173], v[32:47]
	v_pk_add_f32 v[254:255], v[212:213], v[254:255]
	v_pk_add_f32 v[254:255], v[214:215], v[254:255]
	v_pk_add_f32 v[254:255], v[216:217], v[254:255]
	s_waitcnt lgkmcnt(10)
	v_mfma_f32_32x32x16_bf16 v[16:31], v[68:71], v[170:173], v[16:31]
	v_pk_add_f32 v[254:255], v[218:219], v[254:255]
	v_add_f32_e32 v195, v254, v255
	v_add_f32_e32 v167, v195, v167
	s_waitcnt lgkmcnt(8)
	v_mfma_f32_32x32x16_bf16 v[0:15], v[72:75], v[170:173], v[0:15]
	s_waitcnt lgkmcnt(6)
	v_mfma_f32_32x32x16_bf16 v[48:63], v[76:79], v[196:199], v[48:63]
	s_waitcnt lgkmcnt(4)
	v_mfma_f32_32x32x16_bf16 v[32:47], v[240:243], v[196:199], v[32:47]
	s_waitcnt lgkmcnt(2)
	v_mfma_f32_32x32x16_bf16 v[16:31], v[250:253], v[196:199], v[16:31]
	s_waitcnt lgkmcnt(0)
	v_mfma_f32_32x32x16_bf16 v[0:15], v[134:137], v[196:199], v[0:15]
	s_branch .LBB0_550
